# MoBA item loop: K fragments loaded from global memory directly in MFMA operand layout (no LDS staging for K); next K loads issued after the QK MFMAs
# speedup vs baseline: 1.0025x; 1.0025x over previous
; #define LAS __attribute__((address_space(3)))
; __device__ __forceinline__ void sub_load(Sub32& r, const bf16* kt, const bf16* vt, int lane) {
; #pragma unroll
;     for (int i = 0; i < 4; ++i) { r.k[i] = *(const u32x4*)(kt + (i * 64 + lane) * 8); r.v[i] = *(const u32x4*)(vt + (i * 64 + lane) * 8); }
; }
; __device__ __forceinline__ void moba_unit2(lbyte* lds, const bf16* QKV, bf16* AO, unsigned char* part, unsigned char* part3, const float* km2, const float* rel_bias, int b, int hm, int own) {
;     ...
;         unsigned it = 0u; if (lane == 0) it = __hip_atomic_fetch_add(ctr, 1u, __ATOMIC_RELAXED, __HIP_MEMORY_SCOPE_WORKGROUP);
;         it = (unsigned)__builtin_amdgcn_readfirstlane((int)it);
;         if (it >= total) break;
;         const int n = __builtin_amdgcn_readfirstlane((int)itemn[it]);
;         const int c = (int)(it - istart[n]), idx = 32 * c + l31; const bool valid = idx < (int)cnt[n];
;         const unsigned ent = list[n * 256 + (valid ? idx : 32 * c)]; const int qid = ent & 255, slot = ent >> 8, tq = own * 256 + qid;
;         s16x8 qf[4];
; #pragma unroll
;         for (int cc = 0; cc < 4; ++cc) qf[cc] = *(const LAS s16x8*)(lds + MC_Q + qid * KP64 + (16 * cc + 8 * h) * 2);
;         f32x16 o[2];
; #pragma unroll
;         for (int r = 0; r < 16; ++r) { o[0][r] = 0.f; o[1][r] = 0.f; }
;         float m = -1e30f, l = 0.f;
;         moba_span<false>(kbuf, vbuf, Kh, Vh, 256 * n, 8, qf, tq, valid, own * 256, own * 256 + 255, dtab, tab, thr, m, l, o, lane, l31, h);
.LBB0_663:
	s_or_b64 exec, exec, s[8:9]
	v_readfirstlane_b32 s11, v0
	s_mov_b64 s[8:9], -1
	s_waitcnt lgkmcnt(0)
	v_cmp_ge_u32_e32 vcc, s11, v240
	s_cbranch_vccnz .LBB0_658
	s_add_i32 s8, s11, 0
	s_add_i32 s8, s8, 0x1b000
	v_mov_b32_e32 v0, s8
	ds_read_u8 v0, v0
	v_mov_b32_e32 v6, v1
	v_mov_b32_e32 v7, v1
	v_mov_b32_e32 v8, v1
	v_mov_b32_e32 v9, v1
	s_waitcnt lgkmcnt(0)
	v_readfirstlane_b32 s8, v0
	s_lshl_b32 s9, s8, 2
	s_add_i32 s9, s9, 0
	s_add_i32 s14, s9, 0x21080
	v_mov_b32_e32 v0, s14
	ds_read_b32 v0, v0
	s_add_i32 s9, s9, 0x21000
	v_mov_b32_e32 v2, s9
	ds_read_b32 v2, v2
	s_lshl_b32 s22, s8, 8
	s_waitcnt lgkmcnt(1)
	v_sub_u32_e32 v0, s11, v0
	v_lshlrev_b32_e32 v0, 5, v0
	s_lshl_b32 s8, s8, 9
	v_or_b32_e32 v3, v0, v183
	s_add_i32 s14, s8, 0
	s_waitcnt lgkmcnt(0)
	v_cmp_lt_i32_e64 s[8:9], v3, v2
	s_ashr_i32 s23, s22, 31
	v_mov_b32_e32 v10, v1
	v_cndmask_b32_e64 v0, v0, v3, s[8:9]
	v_lshl_add_u32 v0, v0, 1, s14
	s_lshl_b64 s[14:15], s[22:23], 7
	v_add_u32_e32 v0, 0x1d000, v0
	v_lshl_add_u64 v[2:3], v[190:191], 0, s[14:15]
	ds_read_u16 v236, v0
	v_lshl_add_u64 v[4:5], v[192:193], 0, s[14:15]
	v_bfe_u32 v50, v232, 5, 1
	v_and_b32_e32 v51, 31, v232
	v_mul_u32_u24_e32 v51, 0x70, v51
	v_mul_u32_u24_e32 v50, 0x1f0, v50
	v_sub_u32_e32 v52, v51, v50
	v_ashrrev_i32_e32 v53, 31, v52
	v_lshl_add_u64 v[58:59], v[190:191], 0, v[52:53]
	v_lshl_add_u64 v[60:61], v[58:59], 0, s[14:15]
	global_load_dwordx4 v[98:101], v[60:61], off
	global_load_dwordx4 v[106:109], v[60:61], off offset:32
	global_load_dwordx4 v[130:133], v[60:61], off offset:64
	global_load_dwordx4 v[134:137], v[60:61], off offset:96
	global_load_dwordx4 v[122:125], v[4:5], off
	global_load_dwordx4 v[126:129], v[4:5], off offset:1024
	global_load_dwordx4 v[138:141], v[4:5], off offset:2048
	global_load_dwordx4 v[142:145], v[4:5], off offset:3072
	v_mov_b32_e32 v2, v1
	v_mov_b32_e32 v3, v1
	s_waitcnt lgkmcnt(0)
	v_and_b32_e32 v234, 0xff, v236
	v_mad_u32_u24 v0, v234, s73, v242
	ds_read_b128 v[102:105], v0
	ds_read_b128 v[110:113], v0 offset:32
	ds_read_b128 v[114:117], v0 offset:64
	ds_read_b128 v[118:121], v0 offset:96
	v_mov_b32_e32 v0, 0x3e38aa3b
	v_cndmask_b32_e64 v196, 0, v0, s[8:9]
	v_add_u32_e32 v0, s20, v234
	v_subrev_u32_e32 v235, s22, v0
	v_add_u32_e32 v0, v250, v234
	v_mov_b32_e32 v4, v1
	v_mov_b32_e32 v5, v1
	v_mov_b32_e32 v11, v1
	v_mov_b32_e32 v12, v1
	v_mov_b32_e32 v13, v1
	v_mov_b32_e32 v14, v1
	v_mov_b32_e32 v15, v1
	v_mov_b32_e32 v16, v1
	v_mov_b32_e32 v17, v1
	v_mov_b32_e32 v18, v1
	v_mov_b32_e32 v19, v1
	v_mov_b32_e32 v20, v1
	v_mov_b32_e32 v21, v1
	v_mov_b32_e32 v22, v1
	v_mov_b32_e32 v23, v1
	v_mov_b32_e32 v24, v1
	v_mov_b32_e32 v25, v1
	v_mov_b32_e32 v26, v1
	v_mov_b32_e32 v27, v1
	v_mov_b32_e32 v28, v1
	v_mov_b32_e32 v29, v1
	v_mov_b32_e32 v30, v1
	v_mov_b32_e32 v31, v1
	v_subrev_u32_e32 v237, s22, v0
	v_mov_b32_e32 v0, v1
	v_mov_b32_e32 v195, 0
	v_mov_b64_e32 v[32:33], v[30:31]
	s_mov_b32 s11, 0
	v_mov_b32_e32 v197, v196
	s_sub_i32 s14, s20, s22
	s_or_b32 s22, s22, 32
	v_mov_b32_e32 v231, 0xf149f2ca
	v_mov_b64_e32 v[30:31], v[28:29]
	v_mov_b64_e32 v[28:29], v[26:27]
	v_mov_b64_e32 v[26:27], v[24:25]
	v_mov_b64_e32 v[24:25], v[22:23]
	v_mov_b64_e32 v[22:23], v[20:21]
	v_mov_b64_e32 v[20:21], v[18:19]
	v_mov_b64_e32 v[18:19], v[16:17]
	v_mov_b64_e32 v[16:17], v[14:15]
	v_mov_b64_e32 v[14:15], v[12:13]
	v_mov_b64_e32 v[12:13], v[10:11]
	v_mov_b64_e32 v[10:11], v[8:9]
	v_mov_b64_e32 v[8:9], v[6:7]
	v_mov_b64_e32 v[6:7], v[4:5]
	v_mov_b64_e32 v[4:5], v[2:3]
	v_mov_b64_e32 v[2:3], v[0:1]
	v_mov_b32_e32 v198, 0
	v_mov_b32_e32 v199, v195
	v_mov_b32_e32 v200, 0
	v_mov_b32_e32 v201, v195
	v_mov_b32_e32 v202, 0
	v_mov_b32_e32 v203, v195
	v_mov_b32_e32 v204, 0
	v_mov_b32_e32 v205, v195
	v_mov_b32_e32 v206, 0
	v_mov_b32_e32 v207, v195
	v_mov_b32_e32 v210, 0
	v_mov_b32_e32 v211, v195
	v_mov_b32_e32 v212, 0
	v_mov_b32_e32 v213, v195
	v_mov_b32_e32 v214, 0
	v_mov_b32_e32 v215, v195
	v_mov_b32_e32 v208, 0
	v_mov_b32_e32 v209, v195
	v_mov_b32_e32 v216, 0
	v_mov_b32_e32 v217, v195
	v_mov_b32_e32 v218, 0
	v_mov_b32_e32 v219, v195
	v_mov_b32_e32 v220, 0
	v_mov_b32_e32 v221, v195
	v_mov_b32_e32 v222, 0
	v_mov_b32_e32 v223, v195
	v_mov_b32_e32 v224, 0
	v_mov_b32_e32 v225, v195
	v_mov_b32_e32 v226, 0
	v_mov_b32_e32 v227, v195
	v_mov_b32_e32 v228, 0
	v_mov_b32_e32 v229, v195
.LBB0_665:
	s_cmpk_eq_i32 s11, 0xff20
	s_waitcnt vmcnt(0)
	ds_write_b128 v251, v[122:125] offset:41472
	ds_write_b128 v251, v[126:129] offset:42624
	ds_write_b128 v251, v[138:141] offset:43776
	ds_write_b128 v251, v[142:145] offset:44928
	s_cbranch_scc1 .LBB0_667
	s_ashr_i32 s23, s22, 31
	s_lshl_b64 s[24:25], s[22:23], 7
	s_mov_b64 s[44:45], s[24:25]
	v_lshl_add_u64 v[36:37], v[192:193], 0, s[24:25]
	global_load_dwordx4 v[122:125], v[36:37], off
	global_load_dwordx4 v[126:129], v[36:37], off offset:1024
	global_load_dwordx4 v[138:141], v[36:37], off offset:2048
	global_load_dwordx4 v[142:145], v[36:37], off offset:3072
; #define LDS_FENCE() asm volatile("" ::: "memory")
; template <bool CAUSAL> __device__ __forceinline__ void moba_span(lbyte* kbuf, lbyte* vbuf, const bf16* Kh, const bf16* Vh, int kpos0, int nsub, const s16x8* qf, int tq, bool valid, int qlo, int qhi, ...
;     ...
;         s16x8 kf[4], vf[4]; f32x16 s[1];
;         load_k<4>(kf, kbuf, KP64, l31, h); load_v_tr<2>(vf, vbuf, lane); LDS_FENCE();
;         qk1<4>(s[0], kf, qf);
;         const int dmin = qlo - (key0 + 31), dmax = qhi - key0;
;         const int bmin = t5_bucket(dmin > 0 ? dmin : 0), bmax = t5_bucket(dmax > 0 ? dmax : 0);
;         if (!CAUSAL && bmax - bmin <= 1) {
;             const float t0 = tab[bmin], t1 = tab[bmax]; const int th1 = thr[bmax];
;             float mxr = s[0][0];
; #pragma unroll
;             for (int r = 1; r < 16; ++r) mxr = fmaxf(mxr, s[0][r]);
;             mxr = pair_max(mxr);
;             const float cL = valid ? 0.125f * LOG2E : 0.f, bL = valid ? t0 : -INFINITY, mx = valid ? mxr * (0.125f * LOG2E) + fmaxf(t0, t1) : -INFINITY;
;             const bool grow = mx > m + 8.0f; const float mn = grow ? mx : m, off = bL - mn, offB = off + (t1 - t0);
;             if (__any(grow)) { const float alpha = __builtin_amdgcn_exp2f(m - mn); l *= alpha; o[0] = o[0] * alpha; o[1] = o[1] * alpha; }
;             m = mn;
;             const int x1 = (bmax > bmin) ? tq - key0 - th1 : -0x40000000; f32x2_t sum2 = {0.f, 0.f};
; #pragma unroll
;             for (int r = 0; r < 16; r += 2) { const int kk = kkrow(r, h);
;                 const f32x2_t ob = {x1 >= kk ? offB : off, x1 >= kk + 1 ? offB : off}; f32x2_t v = {s[0][r], s[0][r + 1]}; v = v * (f32x2_t){cL, cL} + ob;
;                 const float e0 = __builtin_amdgcn_exp2f(v.x), e1 = __builtin_amdgcn_exp2f(v.y); s[0][r] = e0; s[0][r + 1] = e1; sum2 += (f32x2_t){e0, e1}; }
;             l += pair_sum(sum2.x + sum2.y);
;         } else {
;             float bb[16];
; #pragma unroll
;             for (int r = 0; r < 16; ++r) { int dist = tq - (key0 + kkrow(r, h)); dist = dist > 0 ? dist : 0; bb[r] = dtab[dist < MC_NDT - 1 ? dist : MC_NDT - 1]; }
;             LDS_FENCE();
; #pragma unroll
;             for (int r = 0; r < 16; ++r) { const int dist = tq - (key0 + kkrow(r, h)); const bool ok = valid && (!CAUSAL || dist >= 0); s[0][r] = ok ? s[0][r] * (0.125f * LOG2E) + bb[r] : -INFINITY; }
;             softmax_upd<1, 2>(s, m, l, o);
.LBB0_667:
	ds_read_b64_tr_b16 v[158:159], v253 offset:41472
	ds_read_b64_tr_b16 v[160:161], v253 offset:42048
	ds_read_b64_tr_b16 v[156:157], v253 offset:42112
	ds_read_b64_tr_b16 v[154:155], v253 offset:41536
	v_mfma_f32_32x32x16_bf16 v[66:81], v[98:101], v[102:105], 0
	s_add_i32 s15, s14, s11
	s_sub_i32 s17, s15, 31
	s_max_i32 s23, s17, 16
	s_flbit_i32_b32 s24, s23
	s_lshl_b32 s24, s24, 1
	s_sub_i32 s26, 62, s24
	s_add_i32 s21, s15, 0xff
	s_max_i32 s15, s17, 0
	s_mul_i32 s23, s23, s23
	s_lshl_b32 s24, 2, s26
	v_mfma_f32_32x32x16_bf16 v[66:81], v[106:109], v[110:113], v[66:81]
	s_cmp_ge_u32 s23, s24
	s_cselect_b32 s23, 1, 0
	ds_read_b64_tr_b16 v[150:151], v253 offset:43776
	ds_read_b64_tr_b16 v[152:153], v253 offset:44352
	ds_read_b64_tr_b16 v[148:149], v253 offset:44416
	ds_read_b64_tr_b16 v[146:147], v253 offset:43840
	s_or_b32 s23, s26, s23
	s_min_u32 s23, s23, 23
	s_add_i32 s23, s23, 8
	s_cmp_lt_i32 s17, 16
	v_mfma_f32_32x32x16_bf16 v[66:81], v[130:133], v[114:117], v[66:81]
	s_cselect_b32 s15, s15, s23
	s_max_i32 s23, s21, 16
	s_flbit_i32_b32 s24, s23
	s_lshl_b32 s24, s24, 1
	s_sub_i32 s26, 62, s24
	s_max_i32 s17, s21, 0
	s_mul_i32 s23, s23, s23
	s_lshl_b32 s24, 2, s26
	s_cmp_ge_u32 s23, s24
	s_cselect_b32 s23, 1, 0
	v_mfma_f32_32x32x16_bf16 v[66:81], v[134:137], v[118:121], v[66:81]
	s_or_b32 s23, s26, s23
	s_min_u32 s23, s23, 23
	s_add_i32 s23, s23, 8
	s_cmp_lt_i32 s21, 16
	s_cselect_b32 s17, s17, s23
	s_cmpk_eq_i32 s11, 0xff20
	s_cbranch_scc1 .Lmk_skip
	v_lshl_add_u64 v[60:61], v[58:59], 0, s[44:45]
	global_load_dwordx4 v[98:101], v[60:61], off
	global_load_dwordx4 v[106:109], v[60:61], off offset:32
	global_load_dwordx4 v[130:133], v[60:61], off offset:64
	global_load_dwordx4 v[134:137], v[60:61], off offset:96
.Lmk_skip:
	s_sub_i32 s21, s17, s15
	s_mov_b64 s[24:25], -1
	s_cmp_gt_i32 s21, 1
	v_add_f32_e32 v0, 0x41000000, v231
	s_cbranch_scc0 .LBB0_671
	s_mov_b64 vcc, s[8:9]
	s_mov_b32 s28, 0x3e38aa3b
	v_add_u32_e32 v34, s11, v237
	v_subrev_u32_e32 v34, 27, v34
	v_lshl_add_u32 v50, v34, 2, s82
	ds_read_b32 v35, v50 offset:108
	ds_read_b32 v36, v50 offset:104
	ds_read_b32 v37, v50 offset:100
	ds_read_b32 v38, v50 offset:96
	ds_read_b32 v39, v50 offset:76
	ds_read_b32 v40, v50 offset:72
	ds_read_b32 v41, v50 offset:68
	ds_read_b32 v42, v50 offset:64
	ds_read_b32 v43, v50 offset:44
	ds_read_b32 v44, v50 offset:40
	ds_read_b32 v45, v50 offset:36
	ds_read_b32 v46, v50 offset:32
	ds_read_b32 v47, v50 offset:12
	ds_read_b32 v48, v50 offset:8
	ds_read_b32 v49, v50 offset:4
	ds_read_b32 v34, v50
	s_waitcnt lgkmcnt(14)
	v_fmac_f32_e32 v35, s28, v66
	v_fmac_f32_e32 v36, s28, v67
	v_cndmask_b32_e32 v82, v238, v35, vcc
	v_cndmask_b32_e32 v83, v238, v36, vcc
	s_waitcnt lgkmcnt(13)
	v_fmac_f32_e32 v37, s28, v68
	s_waitcnt lgkmcnt(12)
	v_fmac_f32_e32 v38, s28, v69
	s_waitcnt lgkmcnt(0)
	v_fmac_f32_e32 v34, s28, v81
	v_cndmask_b32_e32 v84, v238, v37, vcc
	v_cndmask_b32_e32 v85, v238, v38, vcc
	v_fmac_f32_e32 v39, s28, v70
	v_fmac_f32_e32 v40, s28, v71
	v_cndmask_b32_e32 v97, v238, v34, vcc
	v_max_f32_e32 v34, v82, v83
	v_cndmask_b32_e32 v86, v238, v39, vcc
	v_cndmask_b32_e32 v87, v238, v40, vcc
	v_fmac_f32_e32 v41, s28, v72
	v_fmac_f32_e32 v42, s28, v73
	v_max3_f32 v34, v34, v84, v85
	v_cndmask_b32_e32 v88, v238, v41, vcc
	v_cndmask_b32_e32 v89, v238, v42, vcc
	v_fmac_f32_e32 v43, s28, v74
	v_fmac_f32_e32 v44, s28, v75
	v_max3_f32 v34, v34, v86, v87
	v_cndmask_b32_e32 v90, v238, v43, vcc
	v_cndmask_b32_e32 v91, v238, v44, vcc
	v_fmac_f32_e32 v45, s28, v76
	v_fmac_f32_e32 v46, s28, v77
	v_max3_f32 v34, v34, v88, v89
	v_cndmask_b32_e32 v92, v238, v45, vcc
	v_cndmask_b32_e32 v93, v238, v46, vcc
	v_fmac_f32_e32 v47, s28, v78
	v_fmac_f32_e32 v48, s28, v79
	v_max3_f32 v34, v34, v90, v91
	v_cndmask_b32_e32 v94, v238, v47, vcc
	v_cndmask_b32_e32 v95, v238, v48, vcc
	v_fmac_f32_e32 v49, s28, v80
	v_max3_f32 v34, v34, v92, v93
	v_cndmask_b32_e32 v96, v238, v49, vcc
	v_max3_f32 v34, v34, v94, v95
	v_max3_f32 v34, v34, v96, v97
	v_mov_b32_e32 v35, v34
	s_nop 1
	v_permlane32_swap_b32_e32 v34, v35
	v_max_f32_e32 v35, v35, v35
	v_max_f32_e32 v34, v34, v34
	v_max_f32_e32 v34, v34, v35
	v_cmp_gt_f32_e32 vcc, v34, v0
	v_mov_b32_e32 v162, v195
	s_nop 0
	v_cndmask_b32_e32 v194, v231, v34, vcc
	s_cbranch_vccz .LBB0_670
	v_sub_f32_e32 v34, v231, v194
	v_exp_f32_e32 v34, v34
	s_nop 0
	v_mul_f32_e32 v162, v195, v34
	v_pk_mul_f32 v[32:33], v[32:33], v[34:35] op_sel_hi:[1,0]
	v_pk_mul_f32 v[30:31], v[30:31], v[34:35] op_sel_hi:[1,0]
	v_pk_mul_f32 v[28:29], v[28:29], v[34:35] op_sel_hi:[1,0]
	v_pk_mul_f32 v[26:27], v[26:27], v[34:35] op_sel_hi:[1,0]
	v_pk_mul_f32 v[24:25], v[24:25], v[34:35] op_sel_hi:[1,0]
	v_pk_mul_f32 v[22:23], v[22:23], v[34:35] op_sel_hi:[1,0]
	v_pk_mul_f32 v[20:21], v[20:21], v[34:35] op_sel_hi:[1,0]
	v_pk_mul_f32 v[16:17], v[16:17], v[34:35] op_sel_hi:[1,0]
	v_pk_mul_f32 v[14:15], v[14:15], v[34:35] op_sel_hi:[1,0]
	v_pk_mul_f32 v[12:13], v[12:13], v[34:35] op_sel_hi:[1,0]
	v_pk_mul_f32 v[10:11], v[10:11], v[34:35] op_sel_hi:[1,0]
	v_pk_mul_f32 v[8:9], v[8:9], v[34:35] op_sel_hi:[1,0]
	v_pk_mul_f32 v[6:7], v[6:7], v[34:35] op_sel_hi:[1,0]
	v_pk_mul_f32 v[4:5], v[4:5], v[34:35] op_sel_hi:[1,0]
	v_pk_mul_f32 v[18:19], v[18:19], v[34:35] op_sel_hi:[1,0]
	v_pk_mul_f32 v[2:3], v[2:3], v[34:35] op_sel_hi:[1,0]
